# top-k: when exactly 16 candidates pass the threshold the compare masks are the selection; tie-break tail skipped
# speedup vs baseline: 1.0015x; 1.0003x over previous
.Ltopk_wr1:
	s_and_saveexec_b64 s[8:9], s[34:35]
	s_cbranch_execz .LBB0_156
	s_add_i32 s14, s3, 0
	s_add_i32 s14, s14, 0x22200
	v_mov_b32_e32 v20, s12
	v_mov_b32_e32 v21, s13
	v_mov_b32_e32 v22, vcc_lo
	v_mov_b32_e32 v23, vcc_hi
	v_mov_b32_e32 v2, s14
	ds_write_b128 v2, v[20:23]
	s_branch .LBB0_156
.Ltopk_fast1:
	s_mov_b64 s[12:13], vcc
	s_mov_b64 vcc, 0
	s_branch .Ltopk_wr1

.Ltopk_wr2:
	s_and_saveexec_b64 s[2:3], s[34:35]
	s_cbranch_execz .LBB0_233
	s_add_i32 s18, s15, 0
	s_add_i32 s18, s18, 0x22200
	v_mov_b32_e32 v20, s12
	v_mov_b32_e32 v21, s13
	v_mov_b32_e32 v22, vcc_lo
	v_mov_b32_e32 v23, vcc_hi
	v_mov_b32_e32 v2, s18
	ds_write_b128 v2, v[20:23]
	s_branch .LBB0_233
.Ltopk_fast2:
	s_mov_b64 s[12:13], s[36:37]
	s_branch .Ltopk_wr2
